# adds mixer-A W_s staging via LDS-DMA, barrier moved to first fragment read
# baseline (speedup 1.0000x reference)
.LBB0_321:
	v_add_u32_e32 v112, s87, v239
	v_ashrrev_i32_e32 v113, 31, v112
	v_lshlrev_b64 v[112:113], 8, v[112:113]
	v_lshl_add_u64 v[112:113], v[218:219], 0, v[112:113]
	s_mov_b32 m0, s97
	s_nop 0
	global_load_lds_dwordx4 v[112:113], off
	v_readlane_b32 s8, v254, 20
	v_readlane_b32 s9, v254, 21
	v_add_u32_e32 v114, s97, v212
	s_andn2_b64 vcc, exec, s[8:9]
	s_cbranch_vccnz .LBB0_323
	s_add_i32 m0, s97, 0x3c0
	s_nop 0
	global_load_lds_dwordx4 v[112:113], off offset:64
.LBB0_323:
	v_cndmask_b32_e64 v115, 0, 1, s[24:25]
	v_cmp_ne_u32_e64 s[8:9], 1, v115
	s_andn2_b64 vcc, exec, s[24:25]
	s_cbranch_vccnz .LBB0_325
	s_add_i32 m0, s97, 0x780
	s_nop 0
	global_load_lds_dwordx4 v[112:113], off offset:128
.LBB0_325:
	v_readlane_b32 s16, v254, 22
	v_readlane_b32 s17, v254, 23
	s_andn2_b64 vcc, exec, s[16:17]
	s_cbranch_vccnz .LBB0_327
	s_add_i32 m0, s97, 0xb40
	s_nop 0
	global_load_lds_dwordx4 v[112:113], off offset:192
.LBB0_327:
	s_lshl_b32 s72, s94, 1
	s_ashr_i32 s11, s10, 31
	s_ashr_i32 s73, s72, 31
	s_lshl_b64 s[16:17], s[72:73], 18
	s_lshl_b64 s[10:11], s[10:11], 15
	v_or_b32_e32 v228, s87, v236
	s_lshl_b32 s94, s94, 8
	s_or_b64 s[40:41], s[10:11], s[14:15]
	v_lshl_add_u64 v[136:137], v[216:217], 0, s[16:17]
	v_ashrrev_i32_e32 v229, 31, v228
	s_ashr_i32 s95, s94, 31
	v_lshl_add_u64 v[152:153], v[136:137], 0, s[40:41]
	s_waitcnt lgkmcnt(0)
	v_lshl_add_u64 v[116:117], v[228:229], 2, s[58:59]
	v_lshl_add_u64 v[154:155], s[94:95], 2, v[214:215]
	v_add_co_u32_e32 v136, vcc, 0x1000, v152
	global_load_dwordx4 v[112:115], v[116:117], off offset:16
	s_nop 0
	global_load_dwordx4 v[116:119], v[116:117], off
	s_nop 0
	global_load_dwordx4 v[192:195], v[154:155], off offset:16
	global_load_dwordx4 v[196:199], v[154:155], off
	v_addc_co_u32_e32 v137, vcc, 0, v153, vcc
	global_load_dwordx4 v[184:187], v[154:155], off offset:144
	global_load_dwordx4 v[188:191], v[154:155], off offset:128
	global_load_dwordx4 v[164:167], v[152:153], off
	global_load_dwordx4 v[148:151], v[152:153], off offset:1024
	global_load_dwordx4 v[160:163], v[136:137], off
	global_load_dwordx4 v[144:147], v[136:137], off offset:1024
	s_and_b64 vcc, exec, s[8:9]
	v_mov_b32_e32 v168, 0
	s_cbranch_vccnz .LBB0_330
	v_add_co_u32_e32 v136, vcc, 0x1000, v152
	global_load_dwordx4 v[172:175], v[154:155], off offset:256
	global_load_dwordx4 v[180:183], v[154:155], off offset:272
	v_addc_co_u32_e32 v137, vcc, 0, v153, vcc
	global_load_dwordx4 v[140:143], v[152:153], off offset:2048
	s_nop 0
	global_load_dwordx4 v[136:139], v[136:137], off offset:2048
	s_and_b64 vcc, exec, s[8:9]
	s_cbranch_vccz .LBB0_331

.LBB0_332:
	s_mov_b32 s10, 0x3856241d
	v_and_b32_e32 v249, 0x7fffffff, v133
	v_and_b32_e32 v248, 0x7fffffff, v132
	v_mov_b64_e32 v[230:231], s[10:11]
	v_pk_fma_f32 v[250:251], v[248:249], s[38:39], v[230:231] op_sel_hi:[1,0,0]
	v_and_b32_e32 v247, 0x7fffffff, v135
	v_pk_fma_f32 v[250:251], v[248:249], v[250:251], s[52:53] op_sel_hi:[1,1,0]
	v_and_b32_e32 v246, 0x7fffffff, v134
	v_pk_fma_f32 v[250:251], v[248:249], v[250:251], s[54:55] op_sel_hi:[1,1,0]
	v_pk_fma_f32 v[252:253], v[246:247], s[38:39], v[230:231] op_sel_hi:[1,0,0]
	v_pk_fma_f32 v[250:251], v[248:249], v[250:251], s[62:63] op_sel_hi:[1,1,0]
	v_pk_fma_f32 v[252:253], v[246:247], v[252:253], s[52:53] op_sel_hi:[1,1,0]
	v_pk_fma_f32 v[250:251], v[248:249], v[250:251], s[82:83] op_sel_hi:[1,1,0]
	v_max_f32_e32 v210, v132, v132
	v_pk_fma_f32 v[248:249], v[248:249], v[250:251], s[84:85] op_sel_hi:[1,1,0]
	v_pk_fma_f32 v[252:253], v[246:247], v[252:253], s[54:55] op_sel_hi:[1,1,0]
	v_pk_mul_f32 v[248:249], v[248:249], v[248:249]
	v_max_f32_e32 v250, 0, v210
	v_pk_mul_f32 v[248:249], v[248:249], v[248:249]
	v_max_f32_e32 v210, v133, v133
	v_pk_mul_f32 v[248:249], v[248:249], v[248:249]
	v_pk_fma_f32 v[252:253], v[246:247], v[252:253], s[62:63] op_sel_hi:[1,1,0]
	v_pk_mul_f32 v[248:249], v[248:249], v[248:249]
	v_max_f32_e32 v251, 0, v210
	v_rcp_f32_e32 v248, v248
	v_rcp_f32_e32 v249, v249
	v_pk_fma_f32 v[252:253], v[246:247], v[252:253], s[82:83] op_sel_hi:[1,1,0]
	v_max_f32_e32 v210, v134, v134
	v_pk_fma_f32 v[246:247], v[246:247], v[252:253], s[84:85] op_sel_hi:[1,1,0]
	v_max_f32_e32 v252, 0, v210
	v_max_f32_e32 v210, v135, v135
	v_max_f32_e32 v253, 0, v210
	v_or_b32_e32 v133, 0x80000000, v133
	v_or_b32_e32 v132, 0x80000000, v132
	v_mul_f32_e32 v210, 0xbfb8aa3b, v128
	v_pk_fma_f32 v[132:133], v[132:133], v[248:249], v[250:251]
	v_exp_f32_e32 v210, v210
	v_mul_f32_e32 v248, 0xbfb8aa3b, v129
	v_exp_f32_e32 v249, v248
	v_pk_mul_f32 v[246:247], v[246:247], v[246:247]
	v_add_f32_e32 v210, 1.0, v210
	v_rcp_f32_e32 v248, v210
	v_add_f32_e32 v210, 1.0, v249
	v_mul_f32_e32 v249, 0xbfb8aa3b, v130
	v_exp_f32_e32 v250, v249
	v_mul_f32_e32 v249, 0xbfb8aa3b, v131
	v_exp_f32_e32 v251, v249
	v_pk_mul_f32 v[246:247], v[246:247], v[246:247]
	v_rcp_f32_e32 v249, v210
	v_pk_mul_f32 v[246:247], v[246:247], v[246:247]
	v_add_f32_e32 v210, 1.0, v250
	v_pk_mul_f32 v[246:247], v[246:247], v[246:247]
	v_rcp_f32_e32 v250, v210
	v_add_f32_e32 v210, 1.0, v251
	v_rcp_f32_e32 v246, v246
	v_rcp_f32_e32 v247, v247
	v_rcp_f32_e32 v251, v210
	v_or_b32_e32 v135, 0x80000000, v135
	v_or_b32_e32 v134, 0x80000000, v134
	v_pk_fma_f32 v[134:135], v[134:135], v[246:247], v[252:253]
	v_pk_mul_f32 v[130:131], v[130:131], v[250:251]
	v_pk_mul_f32 v[128:129], v[128:129], v[248:249]
	v_pk_mul_f32 v[130:131], v[134:135], v[130:131]
	v_and_b32_e32 v135, 0x7fffffff, v125
	v_and_b32_e32 v134, 0x7fffffff, v124
	v_pk_fma_f32 v[246:247], v[134:135], s[38:39], v[230:231] op_sel_hi:[1,0,0]
	v_pk_mul_f32 v[128:129], v[132:133], v[128:129]
	v_pk_fma_f32 v[246:247], v[134:135], v[246:247], s[52:53] op_sel_hi:[1,1,0]
	v_and_b32_e32 v133, 0x7fffffff, v127
	v_pk_fma_f32 v[246:247], v[134:135], v[246:247], s[54:55] op_sel_hi:[1,1,0]
	v_and_b32_e32 v132, 0x7fffffff, v126
	v_pk_fma_f32 v[246:247], v[134:135], v[246:247], s[62:63] op_sel_hi:[1,1,0]
	v_pk_fma_f32 v[248:249], v[132:133], s[38:39], v[230:231] op_sel_hi:[1,0,0]
	v_pk_fma_f32 v[246:247], v[134:135], v[246:247], s[82:83] op_sel_hi:[1,1,0]
	v_pk_fma_f32 v[248:249], v[132:133], v[248:249], s[52:53] op_sel_hi:[1,1,0]
	v_pk_fma_f32 v[134:135], v[134:135], v[246:247], s[84:85] op_sel_hi:[1,1,0]
	v_max_f32_e32 v210, v124, v124
	v_pk_mul_f32 v[134:135], v[134:135], v[134:135]
	v_pk_fma_f32 v[248:249], v[132:133], v[248:249], s[54:55] op_sel_hi:[1,1,0]
	v_pk_mul_f32 v[134:135], v[134:135], v[134:135]
	v_max_f32_e32 v246, 0, v210
	v_pk_mul_f32 v[134:135], v[134:135], v[134:135]
	v_max_f32_e32 v210, v125, v125
	v_pk_mul_f32 v[134:135], v[134:135], v[134:135]
	v_pk_fma_f32 v[248:249], v[132:133], v[248:249], s[62:63] op_sel_hi:[1,1,0]
	v_rcp_f32_e32 v134, v134
	v_rcp_f32_e32 v135, v135
	v_max_f32_e32 v247, 0, v210
	v_pk_fma_f32 v[248:249], v[132:133], v[248:249], s[82:83] op_sel_hi:[1,1,0]
	v_max_f32_e32 v210, v126, v126
	v_pk_fma_f32 v[132:133], v[132:133], v[248:249], s[84:85] op_sel_hi:[1,1,0]
	v_max_f32_e32 v248, 0, v210
	v_max_f32_e32 v210, v127, v127
	v_max_f32_e32 v249, 0, v210
	v_or_b32_e32 v125, 0x80000000, v125
	v_or_b32_e32 v124, 0x80000000, v124
	v_mul_f32_e32 v210, 0xbfb8aa3b, v122
	v_pk_fma_f32 v[124:125], v[124:125], v[134:135], v[246:247]
	v_exp_f32_e32 v210, v210
	v_mul_f32_e32 v246, 0xbfb8aa3b, v123
	v_mul_f32_e32 v134, 0xbfb8aa3b, v120
	v_mul_f32_e32 v135, 0xbfb8aa3b, v121
	v_exp_f32_e32 v247, v246
	v_pk_mul_f32 v[132:133], v[132:133], v[132:133]
	v_exp_f32_e32 v134, v134
	v_exp_f32_e32 v135, v135
	v_pk_mul_f32 v[132:133], v[132:133], v[132:133]
	v_add_f32_e32 v210, 1.0, v210
	v_pk_mul_f32 v[132:133], v[132:133], v[132:133]
	v_rcp_f32_e32 v246, v210
	v_pk_mul_f32 v[132:133], v[132:133], v[132:133]
	v_add_f32_e32 v210, 1.0, v247
	v_rcp_f32_e32 v132, v132
	v_rcp_f32_e32 v133, v133
	v_add_f32_e32 v134, 1.0, v134
	v_add_f32_e32 v135, 1.0, v135
	v_rcp_f32_e32 v247, v210
	v_rcp_f32_e32 v134, v134
	v_rcp_f32_e32 v135, v135
	v_or_b32_e32 v127, 0x80000000, v127
	v_or_b32_e32 v126, 0x80000000, v126
	v_pk_fma_f32 v[126:127], v[126:127], v[132:133], v[248:249]
	v_pk_mul_f32 v[122:123], v[122:123], v[246:247]
	v_pk_mul_f32 v[120:121], v[120:121], v[134:135]
	v_pk_mul_f32 v[122:123], v[126:127], v[122:123]
	v_pk_mul_f32 v[120:121], v[124:125], v[120:121]
	v_cvt_pk_bf16_f32 v127, v128, v129
	v_cvt_pk_bf16_f32 v126, v130, v131
	s_and_b64 vcc, exec, s[8:9]
	v_cvt_pk_bf16_f32 v125, v120, v121
	v_cvt_pk_bf16_f32 v124, v122, v123
	v_and_b32_e32 v123, 0x7fffffff, v109
	v_and_b32_e32 v122, 0x7fffffff, v108
	v_pk_fma_f32 v[128:129], v[122:123], s[38:39], v[230:231] op_sel_hi:[1,0,0]
	v_and_b32_e32 v121, 0x7fffffff, v111
	v_pk_fma_f32 v[128:129], v[122:123], v[128:129], s[52:53] op_sel_hi:[1,1,0]
	v_and_b32_e32 v120, 0x7fffffff, v110
	v_pk_fma_f32 v[128:129], v[122:123], v[128:129], s[54:55] op_sel_hi:[1,1,0]
	v_pk_fma_f32 v[130:131], v[120:121], s[38:39], v[230:231] op_sel_hi:[1,0,0]
	v_pk_fma_f32 v[128:129], v[122:123], v[128:129], s[62:63] op_sel_hi:[1,1,0]
	v_pk_fma_f32 v[130:131], v[120:121], v[130:131], s[52:53] op_sel_hi:[1,1,0]
	v_pk_fma_f32 v[128:129], v[122:123], v[128:129], s[82:83] op_sel_hi:[1,1,0]
	v_pk_fma_f32 v[130:131], v[120:121], v[130:131], s[54:55] op_sel_hi:[1,1,0]
	v_pk_fma_f32 v[122:123], v[122:123], v[128:129], s[84:85] op_sel_hi:[1,1,0]
	v_max_f32_e32 v128, v108, v108
	v_pk_mul_f32 v[122:123], v[122:123], v[122:123]
	v_max_f32_e32 v129, v109, v109
	v_pk_mul_f32 v[122:123], v[122:123], v[122:123]
	v_max_f32_e32 v128, 0, v128
	v_pk_mul_f32 v[122:123], v[122:123], v[122:123]
	v_max_f32_e32 v129, 0, v129
	v_pk_mul_f32 v[122:123], v[122:123], v[122:123]
	v_pk_fma_f32 v[130:131], v[120:121], v[130:131], s[62:63] op_sel_hi:[1,1,0]
	v_rcp_f32_e32 v122, v122
	v_rcp_f32_e32 v123, v123
	v_or_b32_e32 v109, 0x80000000, v109
	v_or_b32_e32 v108, 0x80000000, v108
	v_pk_fma_f32 v[130:131], v[120:121], v[130:131], s[82:83] op_sel_hi:[1,1,0]
	v_pk_fma_f32 v[108:109], v[108:109], v[122:123], v[128:129]
	v_mul_f32_e32 v128, 0xbfb8aa3b, v106
	v_mul_f32_e32 v129, 0xbfb8aa3b, v107
	v_pk_fma_f32 v[120:121], v[120:121], v[130:131], s[84:85] op_sel_hi:[1,1,0]
	v_exp_f32_e32 v128, v128
	v_exp_f32_e32 v129, v129
	v_pk_mul_f32 v[120:121], v[120:121], v[120:121]
	v_max_f32_e32 v130, v110, v110
	v_pk_mul_f32 v[120:121], v[120:121], v[120:121]
	v_add_f32_e32 v128, 1.0, v128
	v_pk_mul_f32 v[120:121], v[120:121], v[120:121]
	v_add_f32_e32 v129, 1.0, v129
	v_pk_mul_f32 v[120:121], v[120:121], v[120:121]
	v_rcp_f32_e32 v128, v128
	v_rcp_f32_e32 v120, v120
	v_rcp_f32_e32 v121, v121
	v_rcp_f32_e32 v129, v129
	v_max_f32_e32 v131, v111, v111
	v_max_f32_e32 v130, 0, v130
	v_max_f32_e32 v131, 0, v131
	v_or_b32_e32 v111, 0x80000000, v111
	v_or_b32_e32 v110, 0x80000000, v110
	v_mul_f32_e32 v122, 0xbfb8aa3b, v104
	v_mul_f32_e32 v123, 0xbfb8aa3b, v105
	v_pk_fma_f32 v[110:111], v[110:111], v[120:121], v[130:131]
	v_pk_mul_f32 v[106:107], v[106:107], v[128:129]
	v_exp_f32_e32 v122, v122
	v_exp_f32_e32 v123, v123
	v_pk_mul_f32 v[106:107], v[110:111], v[106:107]
	v_and_b32_e32 v111, 0x7fffffff, v101
	v_and_b32_e32 v110, 0x7fffffff, v100
	v_pk_fma_f32 v[120:121], v[110:111], s[38:39], v[230:231] op_sel_hi:[1,0,0]
	v_add_f32_e32 v122, 1.0, v122
	v_pk_fma_f32 v[120:121], v[110:111], v[120:121], s[52:53] op_sel_hi:[1,1,0]
	v_add_f32_e32 v123, 1.0, v123
	v_pk_fma_f32 v[120:121], v[110:111], v[120:121], s[54:55] op_sel_hi:[1,1,0]
	v_rcp_f32_e32 v122, v122
	v_pk_fma_f32 v[120:121], v[110:111], v[120:121], s[62:63] op_sel_hi:[1,1,0]
	v_rcp_f32_e32 v123, v123
	v_pk_fma_f32 v[120:121], v[110:111], v[120:121], s[82:83] op_sel_hi:[1,1,0]
	v_pk_mul_f32 v[104:105], v[104:105], v[122:123]
	v_pk_fma_f32 v[110:111], v[110:111], v[120:121], s[84:85] op_sel_hi:[1,1,0]
	v_pk_mul_f32 v[104:105], v[108:109], v[104:105]
	v_pk_mul_f32 v[110:111], v[110:111], v[110:111]
	v_and_b32_e32 v109, 0x7fffffff, v103
	v_pk_mul_f32 v[110:111], v[110:111], v[110:111]
	v_and_b32_e32 v108, 0x7fffffff, v102
	v_pk_mul_f32 v[110:111], v[110:111], v[110:111]
	v_pk_fma_f32 v[122:123], v[108:109], s[38:39], v[230:231] op_sel_hi:[1,0,0]
	v_pk_mul_f32 v[110:111], v[110:111], v[110:111]
	v_pk_fma_f32 v[122:123], v[108:109], v[122:123], s[52:53] op_sel_hi:[1,1,0]
	v_rcp_f32_e32 v110, v110
	v_rcp_f32_e32 v111, v111
	v_max_f32_e32 v120, v100, v100
	v_max_f32_e32 v121, v101, v101
	v_pk_fma_f32 v[122:123], v[108:109], v[122:123], s[54:55] op_sel_hi:[1,1,0]
	v_max_f32_e32 v120, 0, v120
	v_max_f32_e32 v121, 0, v121
	v_pk_fma_f32 v[122:123], v[108:109], v[122:123], s[62:63] op_sel_hi:[1,1,0]
	v_or_b32_e32 v101, 0x80000000, v101
	v_or_b32_e32 v100, 0x80000000, v100
	v_pk_fma_f32 v[122:123], v[108:109], v[122:123], s[82:83] op_sel_hi:[1,1,0]
	v_pk_fma_f32 v[100:101], v[100:101], v[110:111], v[120:121]
	v_mul_f32_e32 v120, 0xbfb8aa3b, v98
	v_mul_f32_e32 v121, 0xbfb8aa3b, v99
	v_pk_fma_f32 v[108:109], v[108:109], v[122:123], s[84:85] op_sel_hi:[1,1,0]
	v_mul_f32_e32 v110, 0xbfb8aa3b, v96
	v_mul_f32_e32 v111, 0xbfb8aa3b, v97
	v_exp_f32_e32 v120, v120
	v_exp_f32_e32 v121, v121
	v_pk_mul_f32 v[108:109], v[108:109], v[108:109]
	v_exp_f32_e32 v110, v110
	v_exp_f32_e32 v111, v111
	v_pk_mul_f32 v[108:109], v[108:109], v[108:109]
	v_add_f32_e32 v120, 1.0, v120
	v_pk_mul_f32 v[108:109], v[108:109], v[108:109]
	v_add_f32_e32 v121, 1.0, v121
	v_pk_mul_f32 v[108:109], v[108:109], v[108:109]
	v_add_f32_e32 v110, 1.0, v110
	v_rcp_f32_e32 v108, v108
	v_rcp_f32_e32 v109, v109
	v_add_f32_e32 v111, 1.0, v111
	v_rcp_f32_e32 v120, v120
	v_rcp_f32_e32 v121, v121
	v_rcp_f32_e32 v110, v110
	v_rcp_f32_e32 v111, v111
	v_max_f32_e32 v122, v102, v102
	v_max_f32_e32 v123, v103, v103
	v_max_f32_e32 v122, 0, v122
	v_max_f32_e32 v123, 0, v123
	v_or_b32_e32 v103, 0x80000000, v103
	v_or_b32_e32 v102, 0x80000000, v102
	v_pk_fma_f32 v[102:103], v[102:103], v[108:109], v[122:123]
	v_pk_mul_f32 v[98:99], v[98:99], v[120:121]
	v_pk_mul_f32 v[96:97], v[96:97], v[110:111]
	v_pk_mul_f32 v[98:99], v[102:103], v[98:99]
	v_pk_mul_f32 v[96:97], v[100:101], v[96:97]
	v_cvt_pk_bf16_f32 v123, v104, v105
	v_cvt_pk_bf16_f32 v122, v106, v107
	s_nop 0
	v_cvt_pk_bf16_f32 v121, v96, v97
	v_cvt_pk_bf16_f32 v120, v98, v99
	v_and_b32_e32 v99, 0x7fffffff, v93
	v_and_b32_e32 v98, 0x7fffffff, v92
	v_pk_fma_f32 v[100:101], v[98:99], s[38:39], v[230:231] op_sel_hi:[1,0,0]
	v_and_b32_e32 v97, 0x7fffffff, v95
	v_pk_fma_f32 v[100:101], v[98:99], v[100:101], s[52:53] op_sel_hi:[1,1,0]
	v_and_b32_e32 v96, 0x7fffffff, v94
	v_pk_fma_f32 v[100:101], v[98:99], v[100:101], s[54:55] op_sel_hi:[1,1,0]
	v_pk_fma_f32 v[102:103], v[96:97], s[38:39], v[230:231] op_sel_hi:[1,0,0]
	v_pk_fma_f32 v[100:101], v[98:99], v[100:101], s[62:63] op_sel_hi:[1,1,0]
	v_pk_fma_f32 v[102:103], v[96:97], v[102:103], s[52:53] op_sel_hi:[1,1,0]
	v_pk_fma_f32 v[100:101], v[98:99], v[100:101], s[82:83] op_sel_hi:[1,1,0]
	v_pk_fma_f32 v[102:103], v[96:97], v[102:103], s[54:55] op_sel_hi:[1,1,0]
	v_pk_fma_f32 v[98:99], v[98:99], v[100:101], s[84:85] op_sel_hi:[1,1,0]
	v_max_f32_e32 v100, v92, v92
	v_pk_mul_f32 v[98:99], v[98:99], v[98:99]
	v_max_f32_e32 v101, v93, v93
	v_pk_mul_f32 v[98:99], v[98:99], v[98:99]
	v_max_f32_e32 v100, 0, v100
	v_pk_mul_f32 v[98:99], v[98:99], v[98:99]
	v_max_f32_e32 v101, 0, v101
	v_pk_mul_f32 v[98:99], v[98:99], v[98:99]
	v_pk_fma_f32 v[102:103], v[96:97], v[102:103], s[62:63] op_sel_hi:[1,1,0]
	v_rcp_f32_e32 v98, v98
	v_rcp_f32_e32 v99, v99
	v_or_b32_e32 v93, 0x80000000, v93
	v_or_b32_e32 v92, 0x80000000, v92
	v_pk_fma_f32 v[102:103], v[96:97], v[102:103], s[82:83] op_sel_hi:[1,1,0]
	v_pk_fma_f32 v[92:93], v[92:93], v[98:99], v[100:101]
	v_mul_f32_e32 v100, 0xbfb8aa3b, v90
	v_mul_f32_e32 v101, 0xbfb8aa3b, v91
	v_pk_fma_f32 v[96:97], v[96:97], v[102:103], s[84:85] op_sel_hi:[1,1,0]
	v_exp_f32_e32 v100, v100
	v_exp_f32_e32 v101, v101
	v_pk_mul_f32 v[96:97], v[96:97], v[96:97]
	v_max_f32_e32 v102, v94, v94
	v_pk_mul_f32 v[96:97], v[96:97], v[96:97]
	v_add_f32_e32 v100, 1.0, v100
	v_pk_mul_f32 v[96:97], v[96:97], v[96:97]
	v_add_f32_e32 v101, 1.0, v101
	v_pk_mul_f32 v[96:97], v[96:97], v[96:97]
	v_rcp_f32_e32 v100, v100
	v_rcp_f32_e32 v96, v96
	v_rcp_f32_e32 v97, v97
	v_rcp_f32_e32 v101, v101
	v_max_f32_e32 v103, v95, v95
	v_max_f32_e32 v102, 0, v102
	v_max_f32_e32 v103, 0, v103
	v_or_b32_e32 v95, 0x80000000, v95
	v_or_b32_e32 v94, 0x80000000, v94
	v_mul_f32_e32 v98, 0xbfb8aa3b, v88
	v_mul_f32_e32 v99, 0xbfb8aa3b, v89
	v_pk_fma_f32 v[94:95], v[94:95], v[96:97], v[102:103]
	v_pk_mul_f32 v[90:91], v[90:91], v[100:101]
	v_exp_f32_e32 v98, v98
	v_exp_f32_e32 v99, v99
	v_pk_mul_f32 v[90:91], v[94:95], v[90:91]
	v_and_b32_e32 v95, 0x7fffffff, v85
	v_and_b32_e32 v94, 0x7fffffff, v84
	v_pk_fma_f32 v[96:97], v[94:95], s[38:39], v[230:231] op_sel_hi:[1,0,0]
	v_add_f32_e32 v98, 1.0, v98
	v_pk_fma_f32 v[96:97], v[94:95], v[96:97], s[52:53] op_sel_hi:[1,1,0]
	v_add_f32_e32 v99, 1.0, v99
	v_pk_fma_f32 v[96:97], v[94:95], v[96:97], s[54:55] op_sel_hi:[1,1,0]
	v_rcp_f32_e32 v98, v98
	v_pk_fma_f32 v[96:97], v[94:95], v[96:97], s[62:63] op_sel_hi:[1,1,0]
	v_rcp_f32_e32 v99, v99
	v_pk_fma_f32 v[96:97], v[94:95], v[96:97], s[82:83] op_sel_hi:[1,1,0]
	v_pk_mul_f32 v[88:89], v[88:89], v[98:99]
	v_pk_fma_f32 v[94:95], v[94:95], v[96:97], s[84:85] op_sel_hi:[1,1,0]
	v_pk_mul_f32 v[88:89], v[92:93], v[88:89]
	v_pk_mul_f32 v[94:95], v[94:95], v[94:95]
	v_and_b32_e32 v93, 0x7fffffff, v87
	v_pk_mul_f32 v[94:95], v[94:95], v[94:95]
	v_and_b32_e32 v92, 0x7fffffff, v86
	v_pk_mul_f32 v[94:95], v[94:95], v[94:95]
	v_pk_fma_f32 v[98:99], v[92:93], s[38:39], v[230:231] op_sel_hi:[1,0,0]
	v_pk_mul_f32 v[94:95], v[94:95], v[94:95]
	v_pk_fma_f32 v[98:99], v[92:93], v[98:99], s[52:53] op_sel_hi:[1,1,0]
	v_rcp_f32_e32 v94, v94
	v_rcp_f32_e32 v95, v95
	v_max_f32_e32 v96, v84, v84
	v_max_f32_e32 v97, v85, v85
	v_pk_fma_f32 v[98:99], v[92:93], v[98:99], s[54:55] op_sel_hi:[1,1,0]
	v_max_f32_e32 v96, 0, v96
	v_max_f32_e32 v97, 0, v97
	v_pk_fma_f32 v[98:99], v[92:93], v[98:99], s[62:63] op_sel_hi:[1,1,0]
	v_or_b32_e32 v85, 0x80000000, v85
	v_or_b32_e32 v84, 0x80000000, v84
	v_pk_fma_f32 v[98:99], v[92:93], v[98:99], s[82:83] op_sel_hi:[1,1,0]
	v_pk_fma_f32 v[84:85], v[84:85], v[94:95], v[96:97]
	v_mul_f32_e32 v94, 0xbfb8aa3b, v80
	v_mul_f32_e32 v95, 0xbfb8aa3b, v81
	v_mul_f32_e32 v96, 0xbfb8aa3b, v82
	v_mul_f32_e32 v97, 0xbfb8aa3b, v83
	v_pk_fma_f32 v[92:93], v[92:93], v[98:99], s[84:85] op_sel_hi:[1,1,0]
	v_exp_f32_e32 v94, v94
	v_exp_f32_e32 v95, v95
	v_exp_f32_e32 v96, v96
	v_exp_f32_e32 v97, v97
	v_pk_mul_f32 v[92:93], v[92:93], v[92:93]
	v_add_f32_e32 v94, 1.0, v94
	v_pk_mul_f32 v[92:93], v[92:93], v[92:93]
	v_add_f32_e32 v95, 1.0, v95
	v_pk_mul_f32 v[92:93], v[92:93], v[92:93]
	v_add_f32_e32 v96, 1.0, v96
	v_pk_mul_f32 v[92:93], v[92:93], v[92:93]
	v_add_f32_e32 v97, 1.0, v97
	v_rcp_f32_e32 v92, v92
	v_rcp_f32_e32 v93, v93
	v_rcp_f32_e32 v94, v94
	v_rcp_f32_e32 v95, v95
	v_rcp_f32_e32 v96, v96
	v_rcp_f32_e32 v97, v97
	v_max_f32_e32 v98, v86, v86
	v_max_f32_e32 v99, v87, v87
	v_max_f32_e32 v98, 0, v98
	v_max_f32_e32 v99, 0, v99
	v_or_b32_e32 v87, 0x80000000, v87
	v_or_b32_e32 v86, 0x80000000, v86
	v_pk_fma_f32 v[86:87], v[86:87], v[92:93], v[98:99]
	v_pk_mul_f32 v[80:81], v[80:81], v[94:95]
	v_pk_mul_f32 v[82:83], v[82:83], v[96:97]
	v_pk_mul_f32 v[80:81], v[84:85], v[80:81]
	v_pk_mul_f32 v[86:87], v[86:87], v[82:83]
	v_cvt_pk_bf16_f32 v83, v88, v89
	v_cvt_pk_bf16_f32 v82, v90, v91
	v_cvt_pk_bf16_f32 v81, v80, v81
	v_and_b32_e32 v85, 0x7fffffff, v79
	v_cvt_pk_bf16_f32 v80, v86, v87
	v_and_b32_e32 v87, 0x7fffffff, v77
	v_and_b32_e32 v86, 0x7fffffff, v76
	v_pk_fma_f32 v[88:89], v[86:87], s[38:39], v[230:231] op_sel_hi:[1,0,0]
	v_and_b32_e32 v84, 0x7fffffff, v78
	v_pk_fma_f32 v[88:89], v[86:87], v[88:89], s[52:53] op_sel_hi:[1,1,0]
	v_pk_fma_f32 v[90:91], v[84:85], s[38:39], v[230:231] op_sel_hi:[1,0,0]
	v_pk_fma_f32 v[88:89], v[86:87], v[88:89], s[54:55] op_sel_hi:[1,1,0]
	v_pk_fma_f32 v[90:91], v[84:85], v[90:91], s[52:53] op_sel_hi:[1,1,0]
	v_pk_fma_f32 v[88:89], v[86:87], v[88:89], s[62:63] op_sel_hi:[1,1,0]
	v_pk_fma_f32 v[90:91], v[84:85], v[90:91], s[54:55] op_sel_hi:[1,1,0]
	v_pk_fma_f32 v[88:89], v[86:87], v[88:89], s[82:83] op_sel_hi:[1,1,0]
	v_pk_fma_f32 v[90:91], v[84:85], v[90:91], s[62:63] op_sel_hi:[1,1,0]
	v_pk_fma_f32 v[86:87], v[86:87], v[88:89], s[84:85] op_sel_hi:[1,1,0]
	v_max_f32_e32 v88, v76, v76
	v_pk_mul_f32 v[86:87], v[86:87], v[86:87]
	v_max_f32_e32 v89, v77, v77
	v_pk_mul_f32 v[86:87], v[86:87], v[86:87]
	v_max_f32_e32 v88, 0, v88
	v_pk_mul_f32 v[86:87], v[86:87], v[86:87]
	v_max_f32_e32 v89, 0, v89
	v_pk_mul_f32 v[86:87], v[86:87], v[86:87]
	v_or_b32_e32 v77, 0x80000000, v77
	v_rcp_f32_e32 v86, v86
	v_rcp_f32_e32 v87, v87
	v_or_b32_e32 v76, 0x80000000, v76
	v_pk_fma_f32 v[90:91], v[84:85], v[90:91], s[82:83] op_sel_hi:[1,1,0]
	s_waitcnt vmcnt(5)
	v_fmamk_f32 v95, v187, 0x3a800000, v245
	v_pk_fma_f32 v[76:77], v[76:77], v[86:87], v[88:89]
	v_mul_f32_e32 v86, 0xbfb8aa3b, v72
	v_mul_f32_e32 v87, 0xbfb8aa3b, v73
	v_exp_f32_e32 v86, v86
	v_exp_f32_e32 v87, v87
	v_pk_fma_f32 v[84:85], v[84:85], v[90:91], s[84:85] op_sel_hi:[1,1,0]
	v_max_f32_e32 v90, v78, v78
	v_pk_mul_f32 v[84:85], v[84:85], v[84:85]
	v_add_f32_e32 v86, 1.0, v86
	v_pk_mul_f32 v[84:85], v[84:85], v[84:85]
	v_add_f32_e32 v87, 1.0, v87
	v_pk_mul_f32 v[84:85], v[84:85], v[84:85]
	v_rcp_f32_e32 v86, v86
	v_rcp_f32_e32 v87, v87
	v_pk_mul_f32 v[84:85], v[84:85], v[84:85]
	v_max_f32_e32 v91, v79, v79
	v_rcp_f32_e32 v84, v84
	v_rcp_f32_e32 v85, v85
	v_pk_mul_f32 v[72:73], v[72:73], v[86:87]
	v_max_f32_e32 v90, 0, v90
	v_max_f32_e32 v91, 0, v91
	v_or_b32_e32 v79, 0x80000000, v79
	v_or_b32_e32 v78, 0x80000000, v78
	v_pk_mul_f32 v[72:73], v[76:77], v[72:73]
	v_and_b32_e32 v77, 0x7fffffff, v69
	v_and_b32_e32 v76, 0x7fffffff, v68
	v_mul_f32_e32 v88, 0xbfb8aa3b, v74
	v_mul_f32_e32 v89, 0xbfb8aa3b, v75
	v_pk_fma_f32 v[78:79], v[78:79], v[84:85], v[90:91]
	v_pk_fma_f32 v[84:85], v[76:77], s[38:39], v[230:231] op_sel_hi:[1,0,0]
	v_exp_f32_e32 v88, v88
	v_exp_f32_e32 v89, v89
	v_pk_fma_f32 v[84:85], v[76:77], v[84:85], s[52:53] op_sel_hi:[1,1,0]
	v_rsq_f32_e32 v95, v95
	v_pk_fma_f32 v[84:85], v[76:77], v[84:85], s[54:55] op_sel_hi:[1,1,0]
	v_add_f32_e32 v88, 1.0, v88
	v_pk_fma_f32 v[84:85], v[76:77], v[84:85], s[62:63] op_sel_hi:[1,1,0]
	v_add_f32_e32 v89, 1.0, v89
	v_pk_fma_f32 v[84:85], v[76:77], v[84:85], s[82:83] op_sel_hi:[1,1,0]
	v_rcp_f32_e32 v88, v88
	v_pk_fma_f32 v[76:77], v[76:77], v[84:85], s[84:85] op_sel_hi:[1,1,0]
	v_rcp_f32_e32 v89, v89
	v_pk_mul_f32 v[76:77], v[76:77], v[76:77]
	v_max_f32_e32 v84, v68, v68
	v_pk_mul_f32 v[76:77], v[76:77], v[76:77]
	v_pk_mul_f32 v[74:75], v[74:75], v[88:89]
	v_pk_mul_f32 v[76:77], v[76:77], v[76:77]
	v_pk_mul_f32 v[78:79], v[78:79], v[74:75]
	v_pk_mul_f32 v[76:77], v[76:77], v[76:77]
	v_and_b32_e32 v75, 0x7fffffff, v71
	v_rcp_f32_e32 v76, v76
	v_rcp_f32_e32 v77, v77
	v_and_b32_e32 v74, 0x7fffffff, v70
	v_max_f32_e32 v85, v69, v69
	v_pk_fma_f32 v[86:87], v[74:75], s[38:39], v[230:231] op_sel_hi:[1,0,0]
	v_max_f32_e32 v84, 0, v84
	v_max_f32_e32 v85, 0, v85
	v_pk_fma_f32 v[86:87], v[74:75], v[86:87], s[52:53] op_sel_hi:[1,1,0]
	v_or_b32_e32 v69, 0x80000000, v69
	v_or_b32_e32 v68, 0x80000000, v68
	v_pk_fma_f32 v[86:87], v[74:75], v[86:87], s[54:55] op_sel_hi:[1,1,0]
	v_pk_fma_f32 v[68:69], v[68:69], v[76:77], v[84:85]
	v_mul_f32_e32 v76, 0xbfb8aa3b, v64
	v_mul_f32_e32 v77, 0xbfb8aa3b, v65
	v_pk_fma_f32 v[86:87], v[74:75], v[86:87], s[62:63] op_sel_hi:[1,1,0]
	v_exp_f32_e32 v76, v76
	v_exp_f32_e32 v77, v77
	v_pk_fma_f32 v[86:87], v[74:75], v[86:87], s[82:83] op_sel_hi:[1,1,0]
	v_mul_f32_e32 v84, 0xbfb8aa3b, v66
	v_pk_fma_f32 v[74:75], v[74:75], v[86:87], s[84:85] op_sel_hi:[1,1,0]
	v_add_f32_e32 v76, 1.0, v76
	v_pk_mul_f32 v[74:75], v[74:75], v[74:75]
	v_add_f32_e32 v77, 1.0, v77
	v_pk_mul_f32 v[74:75], v[74:75], v[74:75]
	v_rcp_f32_e32 v76, v76
	v_pk_mul_f32 v[74:75], v[74:75], v[74:75]
	v_rcp_f32_e32 v77, v77
	v_pk_mul_f32 v[74:75], v[74:75], v[74:75]
	v_max_f32_e32 v86, v70, v70
	v_rcp_f32_e32 v74, v74
	v_rcp_f32_e32 v75, v75
	v_max_f32_e32 v87, v71, v71
	v_pk_mul_f32 v[64:65], v[64:65], v[76:77]
	v_max_f32_e32 v86, 0, v86
	v_max_f32_e32 v87, 0, v87
	v_or_b32_e32 v71, 0x80000000, v71
	v_or_b32_e32 v70, 0x80000000, v70
	v_pk_mul_f32 v[64:65], v[68:69], v[64:65]
	v_pk_fma_f32 v[70:71], v[70:71], v[74:75], v[86:87]
	v_cvt_pk_bf16_f32 v75, v72, v73
	v_cvt_pk_bf16_f32 v74, v78, v79
	v_cvt_pk_bf16_f32 v73, v64, v65
	v_fmamk_f32 v64, v196, 0x3a800000, v245
	v_mul_f32_e32 v85, 0xbfb8aa3b, v67
	v_rsq_f32_e32 v88, v64
	v_fmamk_f32 v64, v192, 0x3a800000, v245
	v_exp_f32_e32 v84, v84
	v_exp_f32_e32 v85, v85
	v_rsq_f32_e32 v87, v64
	v_fmamk_f32 v64, v197, 0x3a800000, v245
	v_rsq_f32_e32 v90, v64
	v_fmamk_f32 v64, v193, 0x3a800000, v245
	v_rsq_f32_e32 v89, v64
	v_fmamk_f32 v64, v198, 0x3a800000, v245
	v_rsq_f32_e32 v92, v64
	v_fmamk_f32 v64, v194, 0x3a800000, v245
	v_add_f32_e32 v84, 1.0, v84
	v_add_f32_e32 v85, 1.0, v85
	v_rsq_f32_e32 v91, v64
	v_fmamk_f32 v64, v199, 0x3a800000, v245
	v_rcp_f32_e32 v84, v84
	v_rcp_f32_e32 v85, v85
	v_rsq_f32_e32 v94, v64
	v_fmamk_f32 v64, v195, 0x3a800000, v245
	v_rsq_f32_e32 v93, v64
	s_waitcnt vmcnt(4)
	v_fmamk_f32 v64, v188, 0x3a800000, v245
	v_rsq_f32_e32 v77, v64
	v_fmamk_f32 v64, v184, 0x3a800000, v245
	v_rsq_f32_e32 v76, v64
	v_fmamk_f32 v64, v189, 0x3a800000, v245
	v_pk_mul_f32 v[66:67], v[66:67], v[84:85]
	v_rsq_f32_e32 v79, v64
	v_fmamk_f32 v64, v185, 0x3a800000, v245
	v_pk_mul_f32 v[66:67], v[70:71], v[66:67]
	v_rsq_f32_e32 v78, v64
	v_fmamk_f32 v64, v190, 0x3a800000, v245
	v_add_u32_e32 v184, s98, v212
	v_cvt_pk_bf16_f32 v72, v66, v67
	v_rsq_f32_e32 v84, v64
	s_barrier
	ds_read_b128 v[64:67], v184
	v_fmamk_f32 v68, v186, 0x3a800000, v245
	v_rsq_f32_e32 v85, v68
	v_fmamk_f32 v68, v191, 0x3a800000, v245
	v_rsq_f32_e32 v86, v68
	s_waitcnt lgkmcnt(0)
	v_lshlrev_b32_e32 v68, 16, v64
	v_and_b32_e32 v64, 0xffff0000, v64
	v_mul_f32_e32 v68, v88, v68
	v_mul_f32_e32 v64, v90, v64
	v_cvt_pk_bf16_f32 v68, v68, v64
	v_lshlrev_b32_e32 v64, 16, v65
	v_and_b32_e32 v65, 0xffff0000, v65
	v_mul_f32_e32 v64, v92, v64
	v_mul_f32_e32 v65, v94, v65
	v_cvt_pk_bf16_f32 v69, v64, v65
	v_lshlrev_b32_e32 v64, 16, v66
	v_and_b32_e32 v65, 0xffff0000, v66
	v_mul_f32_e32 v64, v87, v64
	v_mul_f32_e32 v65, v89, v65
	v_cvt_pk_bf16_f32 v70, v64, v65
	v_lshlrev_b32_e32 v64, 16, v67
	v_and_b32_e32 v65, 0xffff0000, v67
	v_mul_f32_e32 v64, v91, v64
	v_mul_f32_e32 v65, v93, v65
	v_cvt_pk_bf16_f32 v71, v64, v65
	s_waitcnt vmcnt(3)
	v_mfma_f32_16x16x32_bf16 v[64:67], v[164:167], v[68:71], 0
	s_waitcnt vmcnt(1)
	v_mfma_f32_16x16x32_bf16 v[68:71], v[160:163], v[68:71], 0
	s_cbranch_vccnz .LBB0_334
	ds_read_b128 v[96:99], v184 offset:1024
	s_waitcnt lgkmcnt(0)
	v_lshlrev_b32_e32 v100, 16, v96
	v_and_b32_e32 v96, 0xffff0000, v96
	v_mul_f32_e32 v100, v77, v100
	v_mul_f32_e32 v96, v79, v96
	v_cvt_pk_bf16_f32 v96, v100, v96
	v_lshlrev_b32_e32 v100, 16, v97
	v_and_b32_e32 v97, 0xffff0000, v97
	v_mul_f32_e32 v100, v84, v100
	v_mul_f32_e32 v97, v86, v97
	v_cvt_pk_bf16_f32 v97, v100, v97
	v_lshlrev_b32_e32 v100, 16, v98
	v_and_b32_e32 v98, 0xffff0000, v98
	v_mul_f32_e32 v100, v76, v100
	v_mul_f32_e32 v98, v78, v98
	v_cvt_pk_bf16_f32 v98, v100, v98
	v_lshlrev_b32_e32 v100, 16, v99
	v_and_b32_e32 v99, 0xffff0000, v99
	v_mul_f32_e32 v99, v95, v99
	v_mul_f32_e32 v100, v85, v100
	v_cvt_pk_bf16_f32 v99, v100, v99
	s_nop 0
	v_mfma_f32_16x16x32_bf16 v[64:67], v[148:151], v[96:99], v[64:67]
	s_waitcnt vmcnt(0)
	v_mfma_f32_16x16x32_bf16 v[68:71], v[144:147], v[96:99], v[68:71]
